# final RMSNorm exchange: partial-sum slots pre-set to a sentinel in phase 0 and polled directly (no arrival counter, no vmcnt(0) before it, no extra barrier)
# speedup vs baseline: 1.0033x; 1.0033x over previous
; __device__ __forceinline__ void phase_prologue(const Params& P, LAS unsigned char* lds) {
;     ...
;     for (int i = 0; i < 8; ++i) { const int idx = tid + 512 * i, k = idx >> 2, r4 = idx & 3;
;         const f32x4 v = *(const f32x4*)(P.w_in + (size_t)k * NIN + 6144 + 4 * r4);
;         Wl[(4 * r4 + 0) * 1024 + k] = v[0]; Wl[(4 * r4 + 1) * 1024 + k] = v[1]; Wl[(4 * r4 + 2) * 1024 + k] = v[2]; Wl[(4 * r4 + 3) * 1024 + k] = v[3]; }
;     if (blockIdx.x == 0 && tid < 128) { ((unsigned*)(P.ws + WS_FLAG))[tid * 16] = 0u; ((unsigned*)(P.ws + WS_CNT))[tid * 16] = 0u; if (tid == 0) *(unsigned*)P.ws = 0u; }
;     if (blockIdx.x == 0) for (int i = tid; i < 3456; i += 512) ((unsigned*)(P.ws + 16384))[i] = 0u;
.LBB0_14:
	s_or_b64 exec, exec, s[4:5]
	v_mov_b32_e32 v16, v194
	s_mov_b32 s3, 0x8040
	v_lshlrev_b32_e32 v12, 2, v16
	v_and_b32_e32 v13, 12, v12
	v_ashrrev_i32_e32 v0, 2, v16
	s_waitcnt lgkmcnt(0)
	s_lshl_b32 s4, s2, 11
	s_add_u32 s6, s70, 0x1c00000
	s_addc_u32 s7, s71, 0
	s_add_u32 s6, s6, s4
	s_addc_u32 s7, s7, 0
	v_lshlrev_b32_e32 v8, 2, v194
	v_mov_b32_e32 v9, -1
	s_nop 3
	global_store_dword v8, v9, s[6:7]
	v_mov_b64_e32 v[10:11], s[44:45]
	v_mad_i64_i32 v[2:3], s[0:1], v0, s3, v[10:11]
	v_lshlrev_b32_e32 v0, 2, v13
	v_mov_b32_e32 v1, 0
	v_lshl_add_u64 v[2:3], v[2:3], 0, v[0:1]
	s_movk_i32 s4, 0x6000
	v_add_u32_e32 v17, 0x200, v16
	v_add_co_u32_e32 v14, vcc, s4, v2
	v_ashrrev_i32_e32 v2, 2, v17
	s_nop 0
	v_addc_co_u32_e32 v15, vcc, 0, v3, vcc
	v_mad_i64_i32 v[2:3], s[0:1], v2, s3, v[10:11]
	v_lshl_add_u64 v[2:3], v[2:3], 0, v[0:1]
	v_add_co_u32_e32 v18, vcc, s4, v2
	v_add_u32_e32 v42, 0x400, v16
	s_nop 0
	v_addc_co_u32_e32 v19, vcc, 0, v3, vcc
	global_load_dwordx4 v[2:5], v[14:15], off
	global_load_dwordx4 v[6:9], v[18:19], off
	v_ashrrev_i32_e32 v14, 2, v42
	v_mad_i64_i32 v[14:15], s[0:1], v14, s3, v[10:11]
	v_add_u32_e32 v43, 0x600, v16
	v_lshl_add_u64 v[14:15], v[14:15], 0, v[0:1]
	v_ashrrev_i32_e32 v18, 2, v43
	v_add_co_u32_e32 v14, vcc, s4, v14
	v_mad_i64_i32 v[18:19], s[0:1], v18, s3, v[10:11]
	s_nop 0
	v_addc_co_u32_e32 v15, vcc, 0, v15, vcc
	v_lshl_add_u64 v[18:19], v[18:19], 0, v[0:1]
	v_add_co_u32_e32 v26, vcc, s4, v18
	v_add_u32_e32 v44, 0x800, v16
	s_nop 0
	v_addc_co_u32_e32 v27, vcc, 0, v19, vcc
	global_load_dwordx4 v[18:21], v[14:15], off
	global_load_dwordx4 v[22:25], v[26:27], off
	v_ashrrev_i32_e32 v14, 2, v44
	v_mad_i64_i32 v[14:15], s[0:1], v14, s3, v[10:11]
	v_add_u32_e32 v45, 0xa00, v16
	v_lshl_add_u64 v[14:15], v[14:15], 0, v[0:1]
	v_ashrrev_i32_e32 v26, 2, v45
	v_add_co_u32_e32 v14, vcc, s4, v14
	v_mad_i64_i32 v[26:27], s[0:1], v26, s3, v[10:11]
	s_nop 0
	v_addc_co_u32_e32 v15, vcc, 0, v15, vcc
	v_lshl_add_u64 v[26:27], v[26:27], 0, v[0:1]
	v_add_co_u32_e32 v34, vcc, s4, v26
	v_add_u32_e32 v46, 0xc00, v16
	s_nop 0
	v_addc_co_u32_e32 v35, vcc, 0, v27, vcc
	global_load_dwordx4 v[26:29], v[14:15], off
	global_load_dwordx4 v[30:33], v[34:35], off
	v_ashrrev_i32_e32 v14, 2, v46
	v_mad_i64_i32 v[14:15], s[0:1], v14, s3, v[10:11]
	v_lshl_add_u64 v[14:15], v[14:15], 0, v[0:1]
	v_add_co_u32_e32 v14, vcc, s4, v14
	s_nop 1
	v_addc_co_u32_e32 v15, vcc, 0, v15, vcc
	global_load_dwordx4 v[34:37], v[14:15], off
	v_add_u32_e32 v14, 0xe00, v16
	v_ashrrev_i32_e32 v15, 2, v14
	v_mad_i64_i32 v[10:11], s[0:1], v15, s3, v[10:11]
	v_lshl_add_u64 v[10:11], v[10:11], 0, v[0:1]
	v_add_co_u32_e32 v10, vcc, s4, v10
	s_add_i32 s1, 0, 0x12000
	s_nop 0
	v_addc_co_u32_e32 v11, vcc, 0, v11, vcc
	global_load_dwordx4 v[38:41], v[10:11], off
	v_lshl_add_u32 v0, v13, 12, s1
	v_and_b32_e32 v10, -4, v16
	v_add_u32_e32 v10, v0, v10
	s_waitcnt vmcnt(7)
	ds_write2st64_b32 v10, v2, v3 offset1:16
	ds_write2st64_b32 v10, v4, v5 offset0:32 offset1:48
	v_and_b32_e32 v2, -4, v17
	v_add_u32_e32 v2, v0, v2
	s_waitcnt vmcnt(6)
	ds_write2st64_b32 v2, v6, v7 offset1:16
	ds_write2st64_b32 v2, v8, v9 offset0:32 offset1:48
	v_and_b32_e32 v2, -4, v42
	v_add_u32_e32 v2, v0, v2
	s_waitcnt vmcnt(5)
	ds_write2st64_b32 v2, v18, v19 offset1:16
	ds_write2st64_b32 v2, v20, v21 offset0:32 offset1:48
	v_and_b32_e32 v2, -4, v43
	v_add_u32_e32 v2, v0, v2
	s_waitcnt vmcnt(4)
	ds_write2st64_b32 v2, v22, v23 offset1:16
	ds_write2st64_b32 v2, v24, v25 offset0:32 offset1:48
	v_and_b32_e32 v2, -4, v44
	v_add_u32_e32 v2, v0, v2
	s_waitcnt vmcnt(3)
	ds_write2st64_b32 v2, v26, v27 offset1:16
	ds_write2st64_b32 v2, v28, v29 offset0:32 offset1:48
	v_and_b32_e32 v2, -4, v45
	v_add_u32_e32 v2, v0, v2
	s_waitcnt vmcnt(2)
	ds_write2st64_b32 v2, v30, v31 offset1:16
	ds_write2st64_b32 v2, v32, v33 offset0:32 offset1:48
	v_and_b32_e32 v2, -4, v46
	v_add_u32_e32 v2, v0, v2
	s_cmp_eq_u32 s2, 0
	s_movk_i32 s0, 0x80
	s_waitcnt vmcnt(1)
	ds_write2st64_b32 v2, v34, v35 offset1:16
	ds_write2st64_b32 v2, v36, v37 offset0:32 offset1:48
	v_and_b32_e32 v2, -4, v14
	s_cselect_b64 s[82:83], -1, 0
	v_cmp_gt_i32_e32 vcc, s0, v16
	v_add_u32_e32 v0, v0, v2
	s_and_b64 s[6:7], s[82:83], vcc
	s_waitcnt vmcnt(0)
	ds_write2st64_b32 v0, v38, v39 offset1:16
	ds_write2st64_b32 v0, v40, v41 offset0:32 offset1:48
	s_and_saveexec_b64 s[4:5], s[6:7]
	s_cbranch_execz .LBB0_17
	v_lshlrev_b32_e32 v2, 4, v16
	v_ashrrev_i32_e32 v3, 31, v2
	v_lshl_add_u64 v[2:3], v[2:3], 2, s[70:71]
	v_add_co_u32_e32 v4, vcc, 0x1b80000, v2
	s_nop 1
	v_addc_co_u32_e32 v5, vcc, 0, v3, vcc
	v_add_co_u32_e32 v2, vcc, 0x1d00000, v2
	global_store_dword v[4:5], v1, off
	s_nop 0
	v_addc_co_u32_e32 v3, vcc, 0, v3, vcc
	v_cmp_eq_u32_e32 vcc, 0, v16
	global_store_dword v[2:3], v1, off
	s_and_b64 exec, exec, vcc
	s_cbranch_execz .LBB0_17
	v_mov_b32_e32 v0, 0
	global_store_dword v0, v0, s[70:71]

;     __device__ __forceinline__ void operator()(f32x4 (&acc)[2][2][4][2], const pg8::Unit& u, int wr, int wc, int fr, int fq, LAS unsigned char* lds, int wid, int lane) const {
;     ...
;         asm volatile("s_waitcnt vmcnt(0)" ::: "memory");
;         if (lane == 0) __hip_atomic_fetch_add(cnt + 16 * u.pm, 1u, __ATOMIC_RELAXED, __HIP_MEMORY_SCOPE_AGENT);
;         if (wid == 0) { unsigned spins = 0;
;             while ((unsigned)__builtin_amdgcn_readfirstlane(__hip_atomic_load(cnt + 16 * u.pm, __ATOMIC_RELAXED, __HIP_MEMORY_SCOPE_AGENT)) < 32u && ++spins < (1u << 22)) __builtin_amdgcn_s_sleep(2);
;             }
;         asm volatile("s_waitcnt vmcnt(0) lgkmcnt(0)" ::: "memory"); __builtin_amdgcn_s_barrier(); asm volatile("" ::: "memory");
;         if (lane < 32) { const unsigned* sl = xbuf + (size_t)(u.pm * 256 + row) * 4; float t = 0.f;
; #pragma unroll
;             for (int k = 0; k < 4; ++k) t += __uint_as_float(__hip_atomic_load(sl + k, __ATOMIC_RELAXED, __HIP_MEMORY_SCOPE_AGENT));
;             St[row] = 1.0f / sqrtf(t * (1.0f / DM) + RMS_EPS); }
.LBB0_887:
	s_or_b64 exec, exec, s[34:35]
	s_waitcnt lgkmcnt(0)
	s_and_saveexec_b64 s[30:31], s[4:5]
	s_cbranch_execz .LBB0_897
	v_lshl_add_u64 v[0:1], v[0:1], 4, s[14:15]
	s_mov_b32 s23, 0x4000
.Lxg_poll:
	global_load_dwordx4 v[2:5], v[0:1], off sc1
	s_add_i32 s23, s23, -1
	s_waitcnt vmcnt(0)
	v_or3_b32 v6, v2, v3, v4
	v_or_b32_e32 v6, v6, v5
	v_cmp_gt_i32_e32 vcc, 0, v6
	s_cbranch_vccz .Lxg_done
	s_cmp_eq_u32 s23, 0
	s_cbranch_scc1 .Lxg_done
	s_sleep 2
	s_branch .Lxg_poll
.Lxg_done:
	v_add_f32_e32 v1, 0, v2
	v_add_f32_e32 v1, v1, v3
	v_add_f32_e32 v1, v1, v4
	v_add_f32_e32 v0, v1, v5
	v_fmamk_f32 v0, v0, 0x3a800000, v217
	v_mul_f32_e32 v1, 0x4f800000, v0
	v_cmp_gt_f32_e32 vcc, s59, v0
	s_nop 1
	v_cndmask_b32_e32 v0, v0, v1, vcc
	v_sqrt_f32_e32 v1, v0
	s_nop 0
	v_add_u32_e32 v2, -1, v1
	v_add_u32_e32 v3, 1, v1
	v_fma_f32 v4, -v2, v1, v0
	v_fma_f32 v5, -v3, v1, v0
	v_cmp_ge_f32_e64 s[10:11], 0, v4
	s_nop 1
	v_cndmask_b32_e64 v1, v1, v2, s[10:11]
	v_cmp_lt_f32_e64 s[10:11], 0, v5
	s_nop 1
	v_cndmask_b32_e64 v1, v1, v3, s[10:11]
	v_mul_f32_e32 v2, 0x37800000, v1
	v_cndmask_b32_e32 v1, v1, v2, vcc
	v_cmp_class_f32_e32 vcc, v0, v218
	s_nop 1
	v_cndmask_b32_e32 v0, v1, v0, vcc
	v_div_scale_f32 v1, s[10:11], v0, v0, 1.0
	v_rcp_f32_e32 v2, v1
	v_div_scale_f32 v3, vcc, 1.0, v0, 1.0
	v_fma_f32 v4, -v1, v2, 1.0
	v_fmac_f32_e32 v2, v4, v2
	v_mul_f32_e32 v4, v3, v2
	v_fma_f32 v5, -v1, v4, v3
	v_fmac_f32_e32 v4, v5, v2
	v_fma_f32 v1, -v1, v4, v3
	v_div_fmas_f32 v1, v1, v2, v4
	v_div_fixup_f32 v0, v1, v0, 1.0
	ds_write_b32 v210, v0
